# in-proj GEMM epilogue: base address + row-stride adds and two EXEC-masked store passes instead of per-row 64-bit mads and 16 saveexec branches
# baseline (speedup 1.0000x reference)
; __device__ __forceinline__ unsigned pk_bf16(float lo, float hi) { unsigned r; asm volatile("v_cvt_pk_bf16_f32 %0, %1, %2" : "=v"(r) : "v"(lo), "v"(hi)); return r; }
;     __device__ __forceinline__ void operator()(const f32x4 (&acc)[2][2][4][2], const Unit& u, int wr, int wc, int fr, int fq) const {
;     ...
;         for (int ai = 0; ai < 2; ++ai) if (ai == 0 || u.half == 0)
; #pragma unroll
;             for (int m = 0; m < 4; ++m) { const int rr = row0 + ai * HALF + m * 16; bf16_t* rowp = (bf16_t*)u.o + (size_t)rr * u.ldo + col0;
;                 const int k = u.mk + rr; const bool mir = (u.mk >= 0) && (k > 0);
;                 bf16_t* rowm = (bf16_t*)u.p1 + (size_t)(2048 - k) * u.ldo + col0;
; #pragma unroll
;                 for (int bj = 0; bj < 2; ++bj) { if (col0 + bj * HALF < u.cmax) { const f32x4 v0 = acc[ai][bj][m][0], v1 = acc[ai][bj][m][1];
;                     u32x4 w; w.x = pk_bf16(v0[0], v0[1]); w.y = pk_bf16(v0[2], v0[3]); w.z = pk_bf16(v1[0], v1[1]); w.w = pk_bf16(v1[2], v1[3]);
;                     st16_wt(rowp + bj * HALF, w);
;                     if (mir) { const float sg = u.mneg ? -1.f : 1.f; u32x4 w2; w2.x = pk_bf16(v0[0] * sg, v0[1] * sg); w2.y = pk_bf16(v0[2] * sg, v0[3] * sg); w2.z = pk_bf16(v1[0] * sg, v1[1] * sg); w2.w = pk_bf16(v1[2] * sg, v1[3] * sg);
;                         st16_wt(rowm + bj * HALF, w2); } } } }
.LBB0_460:
	v_mbcnt_lo_u32_b32 v0, -1, 0
	v_mbcnt_hi_u32_b32 v0, -1, v0
	s_waitcnt lgkmcnt(0)
	v_and_or_b32 v132, v0, 15, s60
	v_lshrrev_b32_e32 v0, 1, v0
	v_and_or_b32 v133, v0, 24, s61
	v_mad_i64_i32 v[2:3], s[4:5], v132, s3, 0
	v_lshl_add_u64 v[2:3], v[2:3], 1, s[16:17]
	v_lshlrev_b32_e32 v0, 1, v133
	v_lshl_add_u64 v[140:141], v[2:3], 0, v[0:1]
	v_cmp_gt_i32_e64 s[10:11], s46, v133
	v_or_b32_e32 v133, 0x80, v133
	v_cmp_gt_i32_e64 s[12:13], s46, v133
	s_lshl_b32 s4, s3, 5
	s_mov_b32 s5, 0
	s_lshl_b32 vcc_lo, s3, 8
	s_mov_b32 vcc_hi, 0
	v_lshl_add_u64 v[142:143], s[4:5], 0, v[140:141]
	v_lshl_add_u64 v[144:145], s[4:5], 0, v[142:143]
	v_lshl_add_u64 v[146:147], s[4:5], 0, v[144:145]
	v_lshl_add_u64 v[148:149], vcc, 0, v[140:141]
	v_lshl_add_u64 v[150:151], vcc, 0, v[142:143]
	v_lshl_add_u64 v[152:153], vcc, 0, v[144:145]
	v_lshl_add_u64 v[154:155], vcc, 0, v[146:147]
	s_cmp_lg_u64 s[8:9], 0
	s_cselect_b32 s4, 1, 0
	s_mov_b64 exec, s[10:11]
	v_cvt_pk_bf16_f32 v134, v128, v129
	v_cvt_pk_bf16_f32 v135, v130, v131
	v_cvt_pk_bf16_f32 v136, v124, v125
	v_cvt_pk_bf16_f32 v137, v126, v127
	global_store_dwordx4 v[140:141], v[134:137], off
	v_cvt_pk_bf16_f32 v156, v120, v121
	v_cvt_pk_bf16_f32 v157, v122, v123
	v_cvt_pk_bf16_f32 v158, v116, v117
	v_cvt_pk_bf16_f32 v159, v118, v119
	global_store_dwordx4 v[142:143], v[156:159], off
	v_cvt_pk_bf16_f32 v134, v112, v113
	v_cvt_pk_bf16_f32 v135, v114, v115
	v_cvt_pk_bf16_f32 v136, v108, v109
	v_cvt_pk_bf16_f32 v137, v110, v111
	global_store_dwordx4 v[144:145], v[134:137], off
	v_cvt_pk_bf16_f32 v156, v104, v105
	v_cvt_pk_bf16_f32 v157, v106, v107
	v_cvt_pk_bf16_f32 v158, v100, v101
	v_cvt_pk_bf16_f32 v159, v102, v103
	global_store_dwordx4 v[146:147], v[156:159], off
	s_cmp_eq_u32 s4, 1
	s_cbranch_scc1 .Lp2e_h0
	v_cvt_pk_bf16_f32 v134, v64, v65
	v_cvt_pk_bf16_f32 v135, v66, v67
	v_cvt_pk_bf16_f32 v136, v60, v61
	v_cvt_pk_bf16_f32 v137, v62, v63
	global_store_dwordx4 v[148:149], v[134:137], off
	v_cvt_pk_bf16_f32 v156, v56, v57
	v_cvt_pk_bf16_f32 v157, v58, v59
	v_cvt_pk_bf16_f32 v158, v52, v53
	v_cvt_pk_bf16_f32 v159, v54, v55
	global_store_dwordx4 v[150:151], v[156:159], off
	v_cvt_pk_bf16_f32 v134, v48, v49
	v_cvt_pk_bf16_f32 v135, v50, v51
	v_cvt_pk_bf16_f32 v136, v44, v45
	v_cvt_pk_bf16_f32 v137, v46, v47
	global_store_dwordx4 v[152:153], v[134:137], off
	v_cvt_pk_bf16_f32 v156, v40, v41
	v_cvt_pk_bf16_f32 v157, v42, v43
	v_cvt_pk_bf16_f32 v158, v36, v37
	v_cvt_pk_bf16_f32 v159, v38, v39
	global_store_dwordx4 v[154:155], v[156:159], off
.Lp2e_h0:
	s_mov_b64 exec, s[12:13]
	v_cvt_pk_bf16_f32 v134, v96, v97
	v_cvt_pk_bf16_f32 v135, v98, v99
	v_cvt_pk_bf16_f32 v136, v92, v93
	v_cvt_pk_bf16_f32 v137, v94, v95
	global_store_dwordx4 v[140:141], v[134:137], off offset:256
	v_cvt_pk_bf16_f32 v156, v88, v89
	v_cvt_pk_bf16_f32 v157, v90, v91
	v_cvt_pk_bf16_f32 v158, v84, v85
	v_cvt_pk_bf16_f32 v159, v86, v87
	global_store_dwordx4 v[142:143], v[156:159], off offset:256
	v_cvt_pk_bf16_f32 v134, v80, v81
	v_cvt_pk_bf16_f32 v135, v82, v83
	v_cvt_pk_bf16_f32 v136, v76, v77
	v_cvt_pk_bf16_f32 v137, v78, v79
	global_store_dwordx4 v[144:145], v[134:137], off offset:256
	v_cvt_pk_bf16_f32 v156, v72, v73
	v_cvt_pk_bf16_f32 v157, v74, v75
	v_cvt_pk_bf16_f32 v158, v68, v69
	v_cvt_pk_bf16_f32 v159, v70, v71
	global_store_dwordx4 v[146:147], v[156:159], off offset:256
	s_cmp_eq_u32 s4, 1
	s_cbranch_scc1 .Lp2e_h1
	v_cvt_pk_bf16_f32 v134, v32, v33
	v_cvt_pk_bf16_f32 v135, v34, v35
	v_cvt_pk_bf16_f32 v136, v28, v29
	v_cvt_pk_bf16_f32 v137, v30, v31
	global_store_dwordx4 v[148:149], v[134:137], off offset:256
	v_cvt_pk_bf16_f32 v156, v24, v25
	v_cvt_pk_bf16_f32 v157, v26, v27
	v_cvt_pk_bf16_f32 v158, v20, v21
	v_cvt_pk_bf16_f32 v159, v22, v23
	global_store_dwordx4 v[150:151], v[156:159], off offset:256
	v_cvt_pk_bf16_f32 v134, v16, v17
	v_cvt_pk_bf16_f32 v135, v18, v19
	v_cvt_pk_bf16_f32 v136, v12, v13
	v_cvt_pk_bf16_f32 v137, v14, v15
	global_store_dwordx4 v[152:153], v[134:137], off offset:256
	v_cvt_pk_bf16_f32 v156, v8, v9
	v_cvt_pk_bf16_f32 v157, v10, v11
	v_cvt_pk_bf16_f32 v158, v4, v5
	v_cvt_pk_bf16_f32 v159, v6, v7
	global_store_dwordx4 v[154:155], v[156:159], off offset:256
.Lp2e_h1:
	s_mov_b64 exec, -1
	s_add_u32 s4, s42, 0xffffff00
	s_addc_u32 s5, s43, -1
	s_andn2_b64 vcc, exec, s[30:31]
	s_cbranch_vccz .LBB0_408
